# rwkv_prep final loop software-pipelined (row loads one iteration ahead, invariant k_k/k_a/mu loads hoisted); v_rcp instead of IEEE div in proj epilogues
# speedup vs baseline: 1.1038x; 1.0075x over previous
.LBB0_149:
	s_waitcnt lgkmcnt(0)
	v_mov_b32_e32 v66, v166
	s_barrier
	s_cmp_lt_i32 s11, 8
	v_bfe_u32 v68, v66, 5, 1
	v_and_b32_e32 v67, 31, v66
	s_mov_b64 s[6:7], -1
	s_mov_b64 s[28:29], 0
	s_cbranch_scc1 .LBB0_164
	s_cmp_gt_i32 s11, 9
	s_mov_b64 s[4:5], 0
	s_cbranch_scc0 .LBB0_161
	s_cmp_eq_u32 s11, 10
	s_mov_b64 s[4:5], -1
	s_cbranch_scc0 .LBB0_245
	v_or3_b32 v86, s10, v174, v67
	v_lshlrev_b32_e32 v69, 2, v68
	v_add_u32_e32 v64, s55, v142
	v_add_u32_e32 v65, s55, v143
	v_add_u32_e32 v70, s55, v144
	v_add_u32_e32 v71, s55, v145
	v_add_u32_e32 v72, s55, v146
	v_add_u32_e32 v73, s55, v147
	v_add_u32_e32 v74, s55, v150
	v_add_u32_e32 v75, s55, v151
	v_add_u32_e32 v76, s55, v152
	v_add_u32_e32 v87, s55, v153
	v_add_u32_e32 v88, s55, v154
	v_add_u32_e32 v89, s55, v155
	v_add_u32_e32 v90, s55, v156
	v_add_u32_e32 v91, s55, v157
	v_add_u32_e32 v92, s55, v158
	v_add_u32_e32 v93, s55, v159
	v_cmp_gt_u32_e64 s[6:7], s33, v86
	v_or_b32_e32 v85, v69, v64
	v_lshlrev_b32_e32 v128, 2, v86
	v_or_b32_e32 v84, v69, v65
	v_or_b32_e32 v83, v69, v70
	v_or_b32_e32 v82, v69, v71
	v_or_b32_e32 v81, v69, v72
	v_or_b32_e32 v80, v69, v73
	v_or_b32_e32 v79, v69, v74
	v_or_b32_e32 v78, v69, v75
	v_or_b32_e32 v77, v69, v76
	v_or_b32_e32 v76, v69, v87
	v_or_b32_e32 v75, v69, v88
	v_or_b32_e32 v74, v69, v89
	v_or_b32_e32 v73, v69, v90
	v_or_b32_e32 v72, v69, v91
	v_or_b32_e32 v71, v69, v92
	v_or_b32_e32 v70, v69, v93
	s_and_saveexec_b64 s[4:5], s[6:7]
	s_cbranch_execz .LBB0_154
	v_mul_f32_e32 v64, 0xbfb8aa3b, v48
	v_exp_f32_e32 v64, v64
	v_readlane_b32 s36, v254, 13
	v_readlane_b32 s40, v254, 17
	v_readlane_b32 s41, v254, 18
	v_add_f32_e32 v64, 1.0, v64
	v_readlane_b32 s37, v254, 14
	v_readlane_b32 s38, v254, 15
	v_readlane_b32 s39, v254, 16
	v_rcp_f32_e32 v87, v64
	s_nop 0
	v_mov_b64_e32 v[64:65], s[40:41]
	v_mad_i64_i32 v[88:89], s[0:1], v85, s3, v[64:65]
	v_lshl_add_u64 v[88:89], v[88:89], 0, v[128:129]
	v_add_co_u32_e32 v88, vcc, s56, v88
	v_readlane_b32 s42, v254, 19
	s_nop 0
	v_addc_co_u32_e32 v89, vcc, -1, v89, vcc
	global_store_dword v[88:89], v87, off offset:-1024
	v_mul_f32_e32 v87, 0xbfb8aa3b, v49
	v_exp_f32_e32 v87, v87
	v_readlane_b32 s43, v254, 20
	v_readlane_b32 s44, v254, 21
	v_readlane_b32 s45, v254, 22
	v_add_f32_e32 v87, 1.0, v87
	v_readlane_b32 s46, v254, 23
	v_readlane_b32 s47, v254, 24
	v_readlane_b32 s48, v254, 25
	v_rcp_f32_e32 v87, v87
	s_nop 0
	v_mad_i64_i32 v[88:89], s[0:1], v84, s3, v[64:65]
	v_lshl_add_u64 v[88:89], v[88:89], 0, v[128:129]
	v_add_co_u32_e32 v88, vcc, s56, v88
	v_readlane_b32 s49, v254, 26
	s_nop 0
	v_addc_co_u32_e32 v89, vcc, -1, v89, vcc
	global_store_dword v[88:89], v87, off offset:-1024
	v_mul_f32_e32 v87, 0xbfb8aa3b, v50
	v_exp_f32_e32 v87, v87
	v_readlane_b32 s50, v254, 27
	v_readlane_b32 s51, v254, 28
	v_add_f32_e32 v87, 1.0, v87
	s_nop 0
	v_rcp_f32_e32 v87, v87
	s_nop 0
	v_mad_i64_i32 v[88:89], s[0:1], v83, s3, v[64:65]
	v_lshl_add_u64 v[88:89], v[88:89], 0, v[128:129]
	v_add_co_u32_e32 v88, vcc, s56, v88
	s_nop 1
	v_addc_co_u32_e32 v89, vcc, -1, v89, vcc
	global_store_dword v[88:89], v87, off offset:-1024
	v_mul_f32_e32 v87, 0xbfb8aa3b, v51
	v_exp_f32_e32 v87, v87
	s_nop 0
	v_add_f32_e32 v87, 1.0, v87
	s_nop 0
	v_rcp_f32_e32 v87, v87
	s_nop 0
	v_mad_i64_i32 v[88:89], s[0:1], v82, s3, v[64:65]
	v_lshl_add_u64 v[88:89], v[88:89], 0, v[128:129]
	v_add_co_u32_e32 v88, vcc, s56, v88
	s_nop 1
	v_addc_co_u32_e32 v89, vcc, -1, v89, vcc
	global_store_dword v[88:89], v87, off offset:-1024
	v_mul_f32_e32 v87, 0xbfb8aa3b, v52
	v_exp_f32_e32 v87, v87
	s_nop 0
	v_add_f32_e32 v87, 1.0, v87
	s_nop 0
	v_rcp_f32_e32 v87, v87
	s_nop 0
	v_mad_i64_i32 v[88:89], s[0:1], v81, s3, v[64:65]
	v_lshl_add_u64 v[88:89], v[88:89], 0, v[128:129]
	v_add_co_u32_e32 v88, vcc, s56, v88
	s_nop 1
	v_addc_co_u32_e32 v89, vcc, -1, v89, vcc
	global_store_dword v[88:89], v87, off offset:-1024
	v_mul_f32_e32 v87, 0xbfb8aa3b, v53
	v_exp_f32_e32 v87, v87
	s_nop 0
	v_add_f32_e32 v87, 1.0, v87
	s_nop 0
	v_rcp_f32_e32 v87, v87
	s_nop 0
	v_mad_i64_i32 v[88:89], s[0:1], v80, s3, v[64:65]
	v_lshl_add_u64 v[88:89], v[88:89], 0, v[128:129]
	v_add_co_u32_e32 v88, vcc, s56, v88
	s_nop 1
	v_addc_co_u32_e32 v89, vcc, -1, v89, vcc
	global_store_dword v[88:89], v87, off offset:-1024
	v_mul_f32_e32 v87, 0xbfb8aa3b, v54
	v_exp_f32_e32 v87, v87
	s_nop 0
	v_add_f32_e32 v87, 1.0, v87
	s_nop 0
	v_rcp_f32_e32 v87, v87
	s_nop 0
	v_mad_i64_i32 v[88:89], s[0:1], v79, s3, v[64:65]
	v_lshl_add_u64 v[88:89], v[88:89], 0, v[128:129]
	v_add_co_u32_e32 v88, vcc, s56, v88
	s_nop 1
	v_addc_co_u32_e32 v89, vcc, -1, v89, vcc
	global_store_dword v[88:89], v87, off offset:-1024
	v_mul_f32_e32 v87, 0xbfb8aa3b, v55
	v_exp_f32_e32 v87, v87
	s_nop 0
	v_add_f32_e32 v87, 1.0, v87
	s_nop 0
	v_rcp_f32_e32 v87, v87
	s_nop 0
	v_mad_i64_i32 v[88:89], s[0:1], v78, s3, v[64:65]
	v_lshl_add_u64 v[88:89], v[88:89], 0, v[128:129]
	v_add_co_u32_e32 v88, vcc, s56, v88
	s_nop 1
	v_addc_co_u32_e32 v89, vcc, -1, v89, vcc
	global_store_dword v[88:89], v87, off offset:-1024
	v_mul_f32_e32 v87, 0xbfb8aa3b, v56
	v_exp_f32_e32 v87, v87
	s_nop 0
	v_add_f32_e32 v87, 1.0, v87
	s_nop 0
	v_rcp_f32_e32 v87, v87
	s_nop 0
	v_mad_i64_i32 v[88:89], s[0:1], v77, s3, v[64:65]
	v_lshl_add_u64 v[88:89], v[88:89], 0, v[128:129]
	v_add_co_u32_e32 v88, vcc, s56, v88
	s_nop 1
	v_addc_co_u32_e32 v89, vcc, -1, v89, vcc
	global_store_dword v[88:89], v87, off offset:-1024
	v_mul_f32_e32 v87, 0xbfb8aa3b, v57
	v_exp_f32_e32 v87, v87
	s_nop 0
	v_add_f32_e32 v87, 1.0, v87
	s_nop 0
	v_rcp_f32_e32 v87, v87
	s_nop 0
	v_mad_i64_i32 v[88:89], s[0:1], v76, s3, v[64:65]
	v_lshl_add_u64 v[88:89], v[88:89], 0, v[128:129]
	v_add_co_u32_e32 v88, vcc, s56, v88
	s_nop 1
	v_addc_co_u32_e32 v89, vcc, -1, v89, vcc
	global_store_dword v[88:89], v87, off offset:-1024
	v_mul_f32_e32 v87, 0xbfb8aa3b, v58
	v_exp_f32_e32 v87, v87
	s_nop 0
	v_add_f32_e32 v87, 1.0, v87
	s_nop 0
	v_rcp_f32_e32 v87, v87
	s_nop 0
	v_mad_i64_i32 v[88:89], s[0:1], v75, s3, v[64:65]
	v_lshl_add_u64 v[88:89], v[88:89], 0, v[128:129]
	v_add_co_u32_e32 v88, vcc, s56, v88
	s_nop 1
	v_addc_co_u32_e32 v89, vcc, -1, v89, vcc
	global_store_dword v[88:89], v87, off offset:-1024
	v_mul_f32_e32 v87, 0xbfb8aa3b, v59
	v_exp_f32_e32 v87, v87
	s_nop 0
	v_add_f32_e32 v87, 1.0, v87
	s_nop 0
	v_rcp_f32_e32 v87, v87
	s_nop 0
	v_mad_i64_i32 v[88:89], s[0:1], v74, s3, v[64:65]
	v_lshl_add_u64 v[88:89], v[88:89], 0, v[128:129]
	v_add_co_u32_e32 v88, vcc, s56, v88
	s_nop 1
	v_addc_co_u32_e32 v89, vcc, -1, v89, vcc
	global_store_dword v[88:89], v87, off offset:-1024
	v_mul_f32_e32 v87, 0xbfb8aa3b, v60
	v_exp_f32_e32 v87, v87
	s_nop 0
	v_add_f32_e32 v87, 1.0, v87
	s_nop 0
	v_rcp_f32_e32 v87, v87
	s_nop 0
	v_mad_i64_i32 v[88:89], s[0:1], v73, s3, v[64:65]
	v_lshl_add_u64 v[88:89], v[88:89], 0, v[128:129]
	v_add_co_u32_e32 v88, vcc, s56, v88
	s_nop 1
	v_addc_co_u32_e32 v89, vcc, -1, v89, vcc
	global_store_dword v[88:89], v87, off offset:-1024
	v_mul_f32_e32 v87, 0xbfb8aa3b, v61
	v_exp_f32_e32 v87, v87
	s_nop 0
	v_add_f32_e32 v87, 1.0, v87
	s_nop 0
	v_rcp_f32_e32 v87, v87
	s_nop 0
	v_mad_i64_i32 v[88:89], s[0:1], v72, s3, v[64:65]
	v_lshl_add_u64 v[88:89], v[88:89], 0, v[128:129]
	v_add_co_u32_e32 v88, vcc, s56, v88
	s_nop 1
	v_addc_co_u32_e32 v89, vcc, -1, v89, vcc
	global_store_dword v[88:89], v87, off offset:-1024
	v_mul_f32_e32 v87, 0xbfb8aa3b, v62
	v_exp_f32_e32 v87, v87
	s_nop 0
	v_add_f32_e32 v87, 1.0, v87
	s_nop 0
	v_rcp_f32_e32 v87, v87
	s_nop 0
	v_mad_i64_i32 v[88:89], s[0:1], v71, s3, v[64:65]
	v_lshl_add_u64 v[88:89], v[88:89], 0, v[128:129]
	v_add_co_u32_e32 v88, vcc, s56, v88
	v_mad_i64_i32 v[64:65], s[0:1], v70, s3, v[64:65]
	s_nop 0
	v_addc_co_u32_e32 v89, vcc, -1, v89, vcc
	global_store_dword v[88:89], v87, off offset:-1024
	v_mul_f32_e32 v87, 0xbfb8aa3b, v63
	v_exp_f32_e32 v87, v87
	v_lshl_add_u64 v[64:65], v[64:65], 0, v[128:129]
	v_add_f32_e32 v87, 1.0, v87
	s_nop 0
	v_add_co_u32_e32 v64, vcc, 0xfffff000, v64
	v_rcp_f32_e32 v87, v87
	s_nop 0
	s_nop 0
	v_addc_co_u32_e32 v65, vcc, -1, v65, vcc
	global_store_dword v[64:65], v87, off offset:-1024
.LBB0_154:
	s_or_b64 exec, exec, s[4:5]
	v_or_b32_e32 v64, 32, v86
	v_cmp_gt_u32_e64 s[4:5], s33, v64
	s_and_saveexec_b64 s[30:31], s[4:5]
	s_cbranch_execz .LBB0_156
	v_mul_f32_e32 v64, 0xbfb8aa3b, v32
	v_exp_f32_e32 v64, v64
	v_readlane_b32 s36, v254, 13
	v_readlane_b32 s40, v254, 17
	v_readlane_b32 s41, v254, 18
	v_add_f32_e32 v64, 1.0, v64
	v_readlane_b32 s37, v254, 14
	v_readlane_b32 s38, v254, 15
	v_readlane_b32 s39, v254, 16
	v_rcp_f32_e32 v88, v64
	s_nop 0
	v_mov_b64_e32 v[64:65], s[40:41]
	v_mad_i64_i32 v[86:87], s[0:1], v85, s3, v[64:65]
	v_mul_f32_e32 v85, 0xbfb8aa3b, v33
	v_exp_f32_e32 v85, v85
	v_lshl_add_u64 v[86:87], v[86:87], 0, v[128:129]
	v_add_co_u32_e32 v86, vcc, s56, v86
	v_add_f32_e32 v85, 1.0, v85
	s_nop 0
	v_addc_co_u32_e32 v87, vcc, -1, v87, vcc
	global_store_dword v[86:87], v88, off offset:-896
	v_readlane_b32 s42, v254, 19
	v_readlane_b32 s43, v254, 20
	v_readlane_b32 s44, v254, 21
	v_rcp_f32_e32 v86, v85
	s_nop 0
	v_mad_i64_i32 v[84:85], s[0:1], v84, s3, v[64:65]
	v_lshl_add_u64 v[84:85], v[84:85], 0, v[128:129]
	v_add_co_u32_e32 v84, vcc, s56, v84
	v_readlane_b32 s45, v254, 22
	s_nop 0
	v_addc_co_u32_e32 v85, vcc, -1, v85, vcc
	global_store_dword v[84:85], v86, off offset:-896
	v_mul_f32_e32 v84, 0xbfb8aa3b, v34
	v_exp_f32_e32 v84, v84
	v_readlane_b32 s46, v254, 23
	v_readlane_b32 s47, v254, 24
	v_readlane_b32 s48, v254, 25
	v_add_f32_e32 v84, 1.0, v84
	v_readlane_b32 s49, v254, 26
	v_readlane_b32 s50, v254, 27
	v_readlane_b32 s51, v254, 28
	v_rcp_f32_e32 v86, v84
	s_nop 0
	v_mad_i64_i32 v[84:85], s[0:1], v83, s3, v[64:65]
	v_mul_f32_e32 v83, 0xbfb8aa3b, v35
	v_exp_f32_e32 v83, v83
	v_lshl_add_u64 v[84:85], v[84:85], 0, v[128:129]
	v_add_co_u32_e32 v84, vcc, s56, v84
	v_add_f32_e32 v83, 1.0, v83
	s_nop 0
	v_addc_co_u32_e32 v85, vcc, -1, v85, vcc
	global_store_dword v[84:85], v86, off offset:-896
	s_nop 0
	v_rcp_f32_e32 v84, v83
	s_nop 0
	v_mad_i64_i32 v[82:83], s[0:1], v82, s3, v[64:65]
	v_lshl_add_u64 v[82:83], v[82:83], 0, v[128:129]
	v_add_co_u32_e32 v82, vcc, s56, v82
	s_nop 1
	v_addc_co_u32_e32 v83, vcc, -1, v83, vcc
	global_store_dword v[82:83], v84, off offset:-896
	v_mul_f32_e32 v82, 0xbfb8aa3b, v36
	v_exp_f32_e32 v82, v82
	s_nop 0
	v_add_f32_e32 v82, 1.0, v82
	s_nop 0
	v_rcp_f32_e32 v84, v82
	s_nop 0
	v_mad_i64_i32 v[82:83], s[0:1], v81, s3, v[64:65]
	v_mul_f32_e32 v81, 0xbfb8aa3b, v37
	v_exp_f32_e32 v81, v81
	v_lshl_add_u64 v[82:83], v[82:83], 0, v[128:129]
	v_add_co_u32_e32 v82, vcc, s56, v82
	v_add_f32_e32 v81, 1.0, v81
	s_nop 0
	v_addc_co_u32_e32 v83, vcc, -1, v83, vcc
	global_store_dword v[82:83], v84, off offset:-896
	s_nop 0
	v_rcp_f32_e32 v82, v81
	s_nop 0
	v_mad_i64_i32 v[80:81], s[0:1], v80, s3, v[64:65]
	v_lshl_add_u64 v[80:81], v[80:81], 0, v[128:129]
	v_add_co_u32_e32 v80, vcc, s56, v80
	s_nop 1
	v_addc_co_u32_e32 v81, vcc, -1, v81, vcc
	global_store_dword v[80:81], v82, off offset:-896
	v_mul_f32_e32 v80, 0xbfb8aa3b, v38
	v_exp_f32_e32 v80, v80
	s_nop 0
	v_add_f32_e32 v80, 1.0, v80
	s_nop 0
	v_rcp_f32_e32 v82, v80
	s_nop 0
	v_mad_i64_i32 v[80:81], s[0:1], v79, s3, v[64:65]
	v_mul_f32_e32 v79, 0xbfb8aa3b, v39
	v_exp_f32_e32 v79, v79
	v_lshl_add_u64 v[80:81], v[80:81], 0, v[128:129]
	v_add_co_u32_e32 v80, vcc, s56, v80
	v_add_f32_e32 v79, 1.0, v79
	s_nop 0
	v_addc_co_u32_e32 v81, vcc, -1, v81, vcc
	global_store_dword v[80:81], v82, off offset:-896
	s_nop 0
	v_rcp_f32_e32 v80, v79
	s_nop 0
	v_mad_i64_i32 v[78:79], s[0:1], v78, s3, v[64:65]
	v_lshl_add_u64 v[78:79], v[78:79], 0, v[128:129]
	v_add_co_u32_e32 v78, vcc, s56, v78
	s_nop 1
	v_addc_co_u32_e32 v79, vcc, -1, v79, vcc
	global_store_dword v[78:79], v80, off offset:-896
	v_mul_f32_e32 v78, 0xbfb8aa3b, v40
	v_exp_f32_e32 v78, v78
	s_nop 0
	v_add_f32_e32 v78, 1.0, v78
	s_nop 0
	v_rcp_f32_e32 v80, v78
	s_nop 0
	v_mad_i64_i32 v[78:79], s[0:1], v77, s3, v[64:65]
	v_mul_f32_e32 v77, 0xbfb8aa3b, v41
	v_exp_f32_e32 v77, v77
	v_lshl_add_u64 v[78:79], v[78:79], 0, v[128:129]
	v_add_co_u32_e32 v78, vcc, s56, v78
	v_add_f32_e32 v77, 1.0, v77
	s_nop 0
	v_addc_co_u32_e32 v79, vcc, -1, v79, vcc
	global_store_dword v[78:79], v80, off offset:-896
	s_nop 0
	v_rcp_f32_e32 v78, v77
	s_nop 0
	v_mad_i64_i32 v[76:77], s[0:1], v76, s3, v[64:65]
	v_lshl_add_u64 v[76:77], v[76:77], 0, v[128:129]
	v_add_co_u32_e32 v76, vcc, s56, v76
	s_nop 1
	v_addc_co_u32_e32 v77, vcc, -1, v77, vcc
	global_store_dword v[76:77], v78, off offset:-896
	v_mul_f32_e32 v76, 0xbfb8aa3b, v42
	v_exp_f32_e32 v76, v76
	s_nop 0
	v_add_f32_e32 v76, 1.0, v76
	s_nop 0
	v_rcp_f32_e32 v78, v76
	s_nop 0
	v_mad_i64_i32 v[76:77], s[0:1], v75, s3, v[64:65]
	v_mul_f32_e32 v75, 0xbfb8aa3b, v43
	v_exp_f32_e32 v75, v75
	v_lshl_add_u64 v[76:77], v[76:77], 0, v[128:129]
	v_add_co_u32_e32 v76, vcc, s56, v76
	v_add_f32_e32 v75, 1.0, v75
	s_nop 0
	v_addc_co_u32_e32 v77, vcc, -1, v77, vcc
	global_store_dword v[76:77], v78, off offset:-896
	s_nop 0
	v_rcp_f32_e32 v76, v75
	s_nop 0
	v_mad_i64_i32 v[74:75], s[0:1], v74, s3, v[64:65]
	v_lshl_add_u64 v[74:75], v[74:75], 0, v[128:129]
	v_add_co_u32_e32 v74, vcc, s56, v74
	s_nop 1
	v_addc_co_u32_e32 v75, vcc, -1, v75, vcc
	global_store_dword v[74:75], v76, off offset:-896
	v_mul_f32_e32 v74, 0xbfb8aa3b, v44
	v_exp_f32_e32 v74, v74
	s_nop 0
	v_add_f32_e32 v74, 1.0, v74
	s_nop 0
	v_rcp_f32_e32 v76, v74
	s_nop 0
	v_mad_i64_i32 v[74:75], s[0:1], v73, s3, v[64:65]
	v_mul_f32_e32 v73, 0xbfb8aa3b, v45
	v_exp_f32_e32 v73, v73
	v_lshl_add_u64 v[74:75], v[74:75], 0, v[128:129]
	v_add_co_u32_e32 v74, vcc, s56, v74
	v_add_f32_e32 v73, 1.0, v73
	s_nop 0
	v_addc_co_u32_e32 v75, vcc, -1, v75, vcc
	global_store_dword v[74:75], v76, off offset:-896
	s_nop 0
	v_rcp_f32_e32 v74, v73
	s_nop 0
	v_mad_i64_i32 v[72:73], s[0:1], v72, s3, v[64:65]
	v_lshl_add_u64 v[72:73], v[72:73], 0, v[128:129]
	v_add_co_u32_e32 v72, vcc, s56, v72
	s_nop 1
	v_addc_co_u32_e32 v73, vcc, -1, v73, vcc
	global_store_dword v[72:73], v74, off offset:-896
	v_mul_f32_e32 v72, 0xbfb8aa3b, v46
	v_exp_f32_e32 v72, v72
	s_nop 0
	v_add_f32_e32 v72, 1.0, v72
	s_nop 0
	v_rcp_f32_e32 v74, v72
	s_nop 0
	v_mad_i64_i32 v[72:73], s[0:1], v71, s3, v[64:65]
	v_mul_f32_e32 v71, 0xbfb8aa3b, v47
	v_exp_f32_e32 v71, v71
	v_lshl_add_u64 v[72:73], v[72:73], 0, v[128:129]
	v_add_co_u32_e32 v72, vcc, s56, v72
	v_add_f32_e32 v71, 1.0, v71
	s_nop 0
	v_addc_co_u32_e32 v73, vcc, -1, v73, vcc
	global_store_dword v[72:73], v74, off offset:-896
	v_mad_i64_i32 v[64:65], s[0:1], v70, s3, v[64:65]
	v_lshl_add_u64 v[64:65], v[64:65], 0, v[128:129]
	v_add_co_u32_e32 v64, vcc, 0xfffff000, v64
	v_rcp_f32_e32 v71, v71
	s_nop 0
	s_nop 0
	v_addc_co_u32_e32 v65, vcc, -1, v65, vcc
	global_store_dword v[64:65], v71, off offset:-896
.LBB0_156:
	s_or_b64 exec, exec, s[30:31]
	v_add_u32_e32 v64, s55, v160
	v_add_u32_e32 v65, s55, v161
	v_add_u32_e32 v70, s55, v162
	v_add_u32_e32 v71, s55, v163
	v_add_u32_e32 v72, s55, v164
	v_add_u32_e32 v73, s55, v165
	v_add_u32_e32 v74, s55, v180
	v_add_u32_e32 v75, s55, v181
	v_add_u32_e32 v76, s55, v182
	v_add_u32_e32 v85, s55, v183
	v_add_u32_e32 v86, s55, v184
	v_add_u32_e32 v87, s55, v185
	v_add_u32_e32 v88, s55, v186
	v_add_u32_e32 v89, s55, v187
	v_add_u32_e32 v90, s55, v188
	v_add_u32_e32 v91, s55, v189
	v_or_b32_e32 v84, v69, v64
	v_or_b32_e32 v83, v69, v65
	v_or_b32_e32 v82, v69, v70
	v_or_b32_e32 v81, v69, v71
	v_or_b32_e32 v80, v69, v72
	v_or_b32_e32 v79, v69, v73
	v_or_b32_e32 v78, v69, v74
	v_or_b32_e32 v77, v69, v75
	v_or_b32_e32 v76, v69, v76
	v_or_b32_e32 v75, v69, v85
	v_or_b32_e32 v74, v69, v86
	v_or_b32_e32 v73, v69, v87
	v_or_b32_e32 v72, v69, v88
	v_or_b32_e32 v71, v69, v89
	v_or_b32_e32 v70, v69, v90
	v_or_b32_e32 v69, v69, v91
	s_and_saveexec_b64 s[30:31], s[6:7]
	s_cbranch_execz .LBB0_158
	v_mul_f32_e32 v64, 0xbfb8aa3b, v16
	v_exp_f32_e32 v64, v64
	v_readlane_b32 s36, v254, 13
	v_readlane_b32 s40, v254, 17
	v_readlane_b32 s41, v254, 18
	v_add_f32_e32 v64, 1.0, v64
	v_readlane_b32 s37, v254, 14
	v_readlane_b32 s38, v254, 15
	v_readlane_b32 s39, v254, 16
	v_rcp_f32_e32 v85, v64
	s_nop 0
	v_mov_b64_e32 v[64:65], s[40:41]
	v_mad_i64_i32 v[86:87], s[0:1], v84, s3, v[64:65]
	v_lshl_add_u64 v[86:87], v[86:87], 0, v[128:129]
	v_add_co_u32_e32 v86, vcc, s56, v86
	v_readlane_b32 s42, v254, 19
	s_nop 0
	v_addc_co_u32_e32 v87, vcc, -1, v87, vcc
	global_store_dword v[86:87], v85, off offset:-1024
	v_mul_f32_e32 v85, 0xbfb8aa3b, v17
	v_exp_f32_e32 v85, v85
	v_readlane_b32 s43, v254, 20
	v_readlane_b32 s44, v254, 21
	v_readlane_b32 s45, v254, 22
	v_add_f32_e32 v85, 1.0, v85
	v_readlane_b32 s46, v254, 23
	v_readlane_b32 s47, v254, 24
	v_readlane_b32 s48, v254, 25
	v_rcp_f32_e32 v85, v85
	s_nop 0
	v_mad_i64_i32 v[86:87], s[0:1], v83, s3, v[64:65]
	v_lshl_add_u64 v[86:87], v[86:87], 0, v[128:129]
	v_add_co_u32_e32 v86, vcc, s56, v86
	v_readlane_b32 s49, v254, 26
	s_nop 0
	v_addc_co_u32_e32 v87, vcc, -1, v87, vcc
	global_store_dword v[86:87], v85, off offset:-1024
	v_mul_f32_e32 v85, 0xbfb8aa3b, v18
	v_exp_f32_e32 v85, v85
	v_readlane_b32 s50, v254, 27
	v_readlane_b32 s51, v254, 28
	v_add_f32_e32 v85, 1.0, v85
	s_nop 0
	v_rcp_f32_e32 v85, v85
	s_nop 0
	v_mad_i64_i32 v[86:87], s[0:1], v82, s3, v[64:65]
	v_lshl_add_u64 v[86:87], v[86:87], 0, v[128:129]
	v_add_co_u32_e32 v86, vcc, s56, v86
	s_nop 1
	v_addc_co_u32_e32 v87, vcc, -1, v87, vcc
	global_store_dword v[86:87], v85, off offset:-1024
	v_mul_f32_e32 v85, 0xbfb8aa3b, v19
	v_exp_f32_e32 v85, v85
	s_nop 0
	v_add_f32_e32 v85, 1.0, v85
	s_nop 0
	v_rcp_f32_e32 v85, v85
	s_nop 0
	v_mad_i64_i32 v[86:87], s[0:1], v81, s3, v[64:65]
	v_lshl_add_u64 v[86:87], v[86:87], 0, v[128:129]
	v_add_co_u32_e32 v86, vcc, s56, v86
	s_nop 1
	v_addc_co_u32_e32 v87, vcc, -1, v87, vcc
	global_store_dword v[86:87], v85, off offset:-1024
	v_mul_f32_e32 v85, 0xbfb8aa3b, v20
	v_exp_f32_e32 v85, v85
	s_nop 0
	v_add_f32_e32 v85, 1.0, v85
	s_nop 0
	v_rcp_f32_e32 v85, v85
	s_nop 0
	v_mad_i64_i32 v[86:87], s[0:1], v80, s3, v[64:65]
	v_lshl_add_u64 v[86:87], v[86:87], 0, v[128:129]
	v_add_co_u32_e32 v86, vcc, s56, v86
	s_nop 1
	v_addc_co_u32_e32 v87, vcc, -1, v87, vcc
	global_store_dword v[86:87], v85, off offset:-1024
	v_mul_f32_e32 v85, 0xbfb8aa3b, v21
	v_exp_f32_e32 v85, v85
	s_nop 0
	v_add_f32_e32 v85, 1.0, v85
	s_nop 0
	v_rcp_f32_e32 v85, v85
	s_nop 0
	v_mad_i64_i32 v[86:87], s[0:1], v79, s3, v[64:65]
	v_lshl_add_u64 v[86:87], v[86:87], 0, v[128:129]
	v_add_co_u32_e32 v86, vcc, s56, v86
	s_nop 1
	v_addc_co_u32_e32 v87, vcc, -1, v87, vcc
	global_store_dword v[86:87], v85, off offset:-1024
	v_mul_f32_e32 v85, 0xbfb8aa3b, v22
	v_exp_f32_e32 v85, v85
	s_nop 0
	v_add_f32_e32 v85, 1.0, v85
	s_nop 0
	v_rcp_f32_e32 v85, v85
	s_nop 0
	v_mad_i64_i32 v[86:87], s[0:1], v78, s3, v[64:65]
	v_lshl_add_u64 v[86:87], v[86:87], 0, v[128:129]
	v_add_co_u32_e32 v86, vcc, s56, v86
	s_nop 1
	v_addc_co_u32_e32 v87, vcc, -1, v87, vcc
	global_store_dword v[86:87], v85, off offset:-1024
	v_mul_f32_e32 v85, 0xbfb8aa3b, v23
	v_exp_f32_e32 v85, v85
	s_nop 0
	v_add_f32_e32 v85, 1.0, v85
	s_nop 0
	v_rcp_f32_e32 v85, v85
	s_nop 0
	v_mad_i64_i32 v[86:87], s[0:1], v77, s3, v[64:65]
	v_lshl_add_u64 v[86:87], v[86:87], 0, v[128:129]
	v_add_co_u32_e32 v86, vcc, s56, v86
	s_nop 1
	v_addc_co_u32_e32 v87, vcc, -1, v87, vcc
	global_store_dword v[86:87], v85, off offset:-1024
	v_mul_f32_e32 v85, 0xbfb8aa3b, v24
	v_exp_f32_e32 v85, v85
	s_nop 0
	v_add_f32_e32 v85, 1.0, v85
	s_nop 0
	v_rcp_f32_e32 v85, v85
	s_nop 0
	v_mad_i64_i32 v[86:87], s[0:1], v76, s3, v[64:65]
	v_lshl_add_u64 v[86:87], v[86:87], 0, v[128:129]
	v_add_co_u32_e32 v86, vcc, s56, v86
	s_nop 1
	v_addc_co_u32_e32 v87, vcc, -1, v87, vcc
	global_store_dword v[86:87], v85, off offset:-1024
	v_mul_f32_e32 v85, 0xbfb8aa3b, v25
	v_exp_f32_e32 v85, v85
	s_nop 0
	v_add_f32_e32 v85, 1.0, v85
	s_nop 0
	v_rcp_f32_e32 v85, v85
	s_nop 0
	v_mad_i64_i32 v[86:87], s[0:1], v75, s3, v[64:65]
	v_lshl_add_u64 v[86:87], v[86:87], 0, v[128:129]
	v_add_co_u32_e32 v86, vcc, s56, v86
	s_nop 1
	v_addc_co_u32_e32 v87, vcc, -1, v87, vcc
	global_store_dword v[86:87], v85, off offset:-1024
	v_mul_f32_e32 v85, 0xbfb8aa3b, v26
	v_exp_f32_e32 v85, v85
	s_nop 0
	v_add_f32_e32 v85, 1.0, v85
	s_nop 0
	v_rcp_f32_e32 v85, v85
	s_nop 0
	v_mad_i64_i32 v[86:87], s[0:1], v74, s3, v[64:65]
	v_lshl_add_u64 v[86:87], v[86:87], 0, v[128:129]
	v_add_co_u32_e32 v86, vcc, s56, v86
	s_nop 1
	v_addc_co_u32_e32 v87, vcc, -1, v87, vcc
	global_store_dword v[86:87], v85, off offset:-1024
	v_mul_f32_e32 v85, 0xbfb8aa3b, v27
	v_exp_f32_e32 v85, v85
	s_nop 0
	v_add_f32_e32 v85, 1.0, v85
	s_nop 0
	v_rcp_f32_e32 v85, v85
	s_nop 0
	v_mad_i64_i32 v[86:87], s[0:1], v73, s3, v[64:65]
	v_lshl_add_u64 v[86:87], v[86:87], 0, v[128:129]
	v_add_co_u32_e32 v86, vcc, s56, v86
	s_nop 1
	v_addc_co_u32_e32 v87, vcc, -1, v87, vcc
	global_store_dword v[86:87], v85, off offset:-1024
	v_mul_f32_e32 v85, 0xbfb8aa3b, v28
	v_exp_f32_e32 v85, v85
	s_nop 0
	v_add_f32_e32 v85, 1.0, v85
	s_nop 0
	v_rcp_f32_e32 v85, v85
	s_nop 0
	v_mad_i64_i32 v[86:87], s[0:1], v72, s3, v[64:65]
	v_lshl_add_u64 v[86:87], v[86:87], 0, v[128:129]
	v_add_co_u32_e32 v86, vcc, s56, v86
	s_nop 1
	v_addc_co_u32_e32 v87, vcc, -1, v87, vcc
	global_store_dword v[86:87], v85, off offset:-1024
	v_mul_f32_e32 v85, 0xbfb8aa3b, v29
	v_exp_f32_e32 v85, v85
	s_nop 0
	v_add_f32_e32 v85, 1.0, v85
	s_nop 0
	v_rcp_f32_e32 v85, v85
	s_nop 0
	v_mad_i64_i32 v[86:87], s[0:1], v71, s3, v[64:65]
	v_lshl_add_u64 v[86:87], v[86:87], 0, v[128:129]
	v_add_co_u32_e32 v86, vcc, s56, v86
	s_nop 1
	v_addc_co_u32_e32 v87, vcc, -1, v87, vcc
	global_store_dword v[86:87], v85, off offset:-1024
	v_mul_f32_e32 v85, 0xbfb8aa3b, v30
	v_exp_f32_e32 v85, v85
	s_nop 0
	v_add_f32_e32 v85, 1.0, v85
	s_nop 0
	v_rcp_f32_e32 v85, v85
	s_nop 0
	v_mad_i64_i32 v[86:87], s[0:1], v70, s3, v[64:65]
	v_lshl_add_u64 v[86:87], v[86:87], 0, v[128:129]
	v_add_co_u32_e32 v86, vcc, s56, v86
	v_mad_i64_i32 v[64:65], s[0:1], v69, s3, v[64:65]
	s_nop 0
	v_addc_co_u32_e32 v87, vcc, -1, v87, vcc
	global_store_dword v[86:87], v85, off offset:-1024
	v_mul_f32_e32 v85, 0xbfb8aa3b, v31
	v_exp_f32_e32 v85, v85
	v_lshl_add_u64 v[64:65], v[64:65], 0, v[128:129]
	v_add_f32_e32 v85, 1.0, v85
	s_nop 0
	v_add_co_u32_e32 v64, vcc, 0xfffff000, v64
	v_rcp_f32_e32 v85, v85
	s_nop 0
	s_nop 0
	v_addc_co_u32_e32 v65, vcc, -1, v65, vcc
	global_store_dword v[64:65], v85, off offset:-1024
.LBB0_158:
	s_or_b64 exec, exec, s[30:31]
	s_and_saveexec_b64 s[6:7], s[4:5]
	s_cbranch_execz .LBB0_160
	v_mul_f32_e32 v64, 0xbfb8aa3b, v0
	v_exp_f32_e32 v64, v64
	v_readlane_b32 s36, v254, 13
	v_readlane_b32 s40, v254, 17
	v_readlane_b32 s41, v254, 18
	v_add_f32_e32 v64, 1.0, v64
	v_readlane_b32 s37, v254, 14
	v_readlane_b32 s38, v254, 15
	v_readlane_b32 s39, v254, 16
	v_rcp_f32_e32 v86, v64
	s_nop 0
	v_mov_b64_e32 v[64:65], s[40:41]
	v_mad_i64_i32 v[84:85], s[0:1], v84, s3, v[64:65]
	v_lshl_add_u64 v[84:85], v[84:85], 0, v[128:129]
	v_add_co_u32_e32 v84, vcc, s56, v84
	v_readlane_b32 s42, v254, 19
	s_nop 0
	v_addc_co_u32_e32 v85, vcc, -1, v85, vcc
	global_store_dword v[84:85], v86, off offset:-896
	v_mul_f32_e32 v84, 0xbfb8aa3b, v1
	v_exp_f32_e32 v84, v84
	v_readlane_b32 s43, v254, 20
	v_readlane_b32 s44, v254, 21
	v_readlane_b32 s45, v254, 22
	v_add_f32_e32 v84, 1.0, v84
	v_readlane_b32 s46, v254, 23
	v_readlane_b32 s47, v254, 24
	v_readlane_b32 s48, v254, 25
	v_rcp_f32_e32 v86, v84
	s_nop 0
	v_mad_i64_i32 v[84:85], s[0:1], v83, s3, v[64:65]
	v_mul_f32_e32 v83, 0xbfb8aa3b, v2
	v_exp_f32_e32 v83, v83
	v_lshl_add_u64 v[84:85], v[84:85], 0, v[128:129]
	v_add_co_u32_e32 v84, vcc, s56, v84
	v_add_f32_e32 v83, 1.0, v83
	s_nop 0
	v_addc_co_u32_e32 v85, vcc, -1, v85, vcc
	global_store_dword v[84:85], v86, off offset:-896
	v_readlane_b32 s49, v254, 26
	v_readlane_b32 s50, v254, 27
	v_readlane_b32 s51, v254, 28
	v_rcp_f32_e32 v84, v83
	s_nop 0
	v_mad_i64_i32 v[82:83], s[0:1], v82, s3, v[64:65]
	v_lshl_add_u64 v[82:83], v[82:83], 0, v[128:129]
	v_add_co_u32_e32 v82, vcc, s56, v82
	s_nop 1
	v_addc_co_u32_e32 v83, vcc, -1, v83, vcc
	global_store_dword v[82:83], v84, off offset:-896
	v_mul_f32_e32 v82, 0xbfb8aa3b, v3
	v_exp_f32_e32 v82, v82
	s_nop 0
	v_add_f32_e32 v82, 1.0, v82
	s_nop 0
	v_rcp_f32_e32 v84, v82
	s_nop 0
	v_mad_i64_i32 v[82:83], s[0:1], v81, s3, v[64:65]
	v_mul_f32_e32 v81, 0xbfb8aa3b, v4
	v_exp_f32_e32 v81, v81
	v_lshl_add_u64 v[82:83], v[82:83], 0, v[128:129]
	v_add_co_u32_e32 v82, vcc, s56, v82
	v_add_f32_e32 v81, 1.0, v81
	s_nop 0
	v_addc_co_u32_e32 v83, vcc, -1, v83, vcc
	global_store_dword v[82:83], v84, off offset:-896
	s_nop 0
	v_rcp_f32_e32 v82, v81
	s_nop 0
	v_mad_i64_i32 v[80:81], s[0:1], v80, s3, v[64:65]
	v_lshl_add_u64 v[80:81], v[80:81], 0, v[128:129]
	v_add_co_u32_e32 v80, vcc, s56, v80
	s_nop 1
	v_addc_co_u32_e32 v81, vcc, -1, v81, vcc
	global_store_dword v[80:81], v82, off offset:-896
	v_mul_f32_e32 v80, 0xbfb8aa3b, v5
	v_exp_f32_e32 v80, v80
	s_nop 0
	v_add_f32_e32 v80, 1.0, v80
	s_nop 0
	v_rcp_f32_e32 v82, v80
	s_nop 0
	v_mad_i64_i32 v[80:81], s[0:1], v79, s3, v[64:65]
	v_mul_f32_e32 v79, 0xbfb8aa3b, v6
	v_exp_f32_e32 v79, v79
	v_lshl_add_u64 v[80:81], v[80:81], 0, v[128:129]
	v_add_co_u32_e32 v80, vcc, s56, v80
	v_add_f32_e32 v79, 1.0, v79
	s_nop 0
	v_addc_co_u32_e32 v81, vcc, -1, v81, vcc
	global_store_dword v[80:81], v82, off offset:-896
	s_nop 0
	v_rcp_f32_e32 v80, v79
	s_nop 0
	v_mad_i64_i32 v[78:79], s[0:1], v78, s3, v[64:65]
	v_lshl_add_u64 v[78:79], v[78:79], 0, v[128:129]
	v_add_co_u32_e32 v78, vcc, s56, v78
	s_nop 1
	v_addc_co_u32_e32 v79, vcc, -1, v79, vcc
	global_store_dword v[78:79], v80, off offset:-896
	v_mul_f32_e32 v78, 0xbfb8aa3b, v7
	v_exp_f32_e32 v78, v78
	s_nop 0
	v_add_f32_e32 v78, 1.0, v78
	s_nop 0
	v_rcp_f32_e32 v80, v78
	s_nop 0
	v_mad_i64_i32 v[78:79], s[0:1], v77, s3, v[64:65]
	v_mul_f32_e32 v77, 0xbfb8aa3b, v8
	v_exp_f32_e32 v77, v77
	v_lshl_add_u64 v[78:79], v[78:79], 0, v[128:129]
	v_add_co_u32_e32 v78, vcc, s56, v78
	v_add_f32_e32 v77, 1.0, v77
	s_nop 0
	v_addc_co_u32_e32 v79, vcc, -1, v79, vcc
	global_store_dword v[78:79], v80, off offset:-896
	s_nop 0
	v_rcp_f32_e32 v78, v77
	s_nop 0
	v_mad_i64_i32 v[76:77], s[0:1], v76, s3, v[64:65]
	v_lshl_add_u64 v[76:77], v[76:77], 0, v[128:129]
	v_add_co_u32_e32 v76, vcc, s56, v76
	s_nop 1
	v_addc_co_u32_e32 v77, vcc, -1, v77, vcc
	global_store_dword v[76:77], v78, off offset:-896
	v_mul_f32_e32 v76, 0xbfb8aa3b, v9
	v_exp_f32_e32 v76, v76
	s_nop 0
	v_add_f32_e32 v76, 1.0, v76
	s_nop 0
	v_rcp_f32_e32 v78, v76
	s_nop 0
	v_mad_i64_i32 v[76:77], s[0:1], v75, s3, v[64:65]
	v_mul_f32_e32 v75, 0xbfb8aa3b, v10
	v_exp_f32_e32 v75, v75
	v_lshl_add_u64 v[76:77], v[76:77], 0, v[128:129]
	v_add_co_u32_e32 v76, vcc, s56, v76
	v_add_f32_e32 v75, 1.0, v75
	s_nop 0
	v_addc_co_u32_e32 v77, vcc, -1, v77, vcc
	global_store_dword v[76:77], v78, off offset:-896
	s_nop 0
	v_rcp_f32_e32 v76, v75
	s_nop 0
	v_mad_i64_i32 v[74:75], s[0:1], v74, s3, v[64:65]
	v_lshl_add_u64 v[74:75], v[74:75], 0, v[128:129]
	v_add_co_u32_e32 v74, vcc, s56, v74
	s_nop 1
	v_addc_co_u32_e32 v75, vcc, -1, v75, vcc
	global_store_dword v[74:75], v76, off offset:-896
	v_mul_f32_e32 v74, 0xbfb8aa3b, v11
	v_exp_f32_e32 v74, v74
	s_nop 0
	v_add_f32_e32 v74, 1.0, v74
	s_nop 0
	v_rcp_f32_e32 v76, v74
	s_nop 0
	v_mad_i64_i32 v[74:75], s[0:1], v73, s3, v[64:65]
	v_mul_f32_e32 v73, 0xbfb8aa3b, v12
	v_exp_f32_e32 v73, v73
	v_lshl_add_u64 v[74:75], v[74:75], 0, v[128:129]
	v_add_co_u32_e32 v74, vcc, s56, v74
	v_add_f32_e32 v73, 1.0, v73
	s_nop 0
	v_addc_co_u32_e32 v75, vcc, -1, v75, vcc
	global_store_dword v[74:75], v76, off offset:-896
	s_nop 0
	v_rcp_f32_e32 v74, v73
	s_nop 0
	v_mad_i64_i32 v[72:73], s[0:1], v72, s3, v[64:65]
	v_lshl_add_u64 v[72:73], v[72:73], 0, v[128:129]
	v_add_co_u32_e32 v72, vcc, s56, v72
	s_nop 1
	v_addc_co_u32_e32 v73, vcc, -1, v73, vcc
	global_store_dword v[72:73], v74, off offset:-896
	v_mul_f32_e32 v72, 0xbfb8aa3b, v13
	v_exp_f32_e32 v72, v72
	s_nop 0
	v_add_f32_e32 v72, 1.0, v72
	s_nop 0
	v_rcp_f32_e32 v74, v72
	s_nop 0
	v_mad_i64_i32 v[72:73], s[0:1], v71, s3, v[64:65]
	v_mul_f32_e32 v71, 0xbfb8aa3b, v14
	v_exp_f32_e32 v71, v71
	v_lshl_add_u64 v[72:73], v[72:73], 0, v[128:129]
	v_add_co_u32_e32 v72, vcc, s56, v72
	v_add_f32_e32 v71, 1.0, v71
	s_nop 0
	v_addc_co_u32_e32 v73, vcc, -1, v73, vcc
	global_store_dword v[72:73], v74, off offset:-896
	s_nop 0
	v_rcp_f32_e32 v72, v71
	s_nop 0
	v_mad_i64_i32 v[70:71], s[0:1], v70, s3, v[64:65]
	v_lshl_add_u64 v[70:71], v[70:71], 0, v[128:129]
	v_add_co_u32_e32 v70, vcc, s56, v70
	v_mad_i64_i32 v[64:65], s[0:1], v69, s3, v[64:65]
	s_nop 0
	v_addc_co_u32_e32 v71, vcc, -1, v71, vcc
	global_store_dword v[70:71], v72, off offset:-896
	v_mul_f32_e32 v70, 0xbfb8aa3b, v15
	v_exp_f32_e32 v70, v70
	v_lshl_add_u64 v[64:65], v[64:65], 0, v[128:129]
	v_add_f32_e32 v70, 1.0, v70
	s_nop 0
	v_add_co_u32_e32 v64, vcc, 0xfffff000, v64
	v_rcp_f32_e32 v70, v70
	s_nop 0
	s_nop 0
	v_addc_co_u32_e32 v65, vcc, -1, v65, vcc
	global_store_dword v[64:65], v70, off offset:-896

.LBB0_171:
	s_andn2_b64 vcc, exec, s[4:5]
	v_mov_b32_e32 v71, v15
	s_cbranch_vccnz .LBB0_173
	v_mul_f32_e32 v71, 0xbfb8aa3b, v48
	v_exp_f32_e32 v71, v71
	s_nop 0
	v_add_f32_e32 v71, 1.0, v71
	s_nop 0
	v_rcp_f32_e32 v73, v71
	s_nop 0
	v_mul_f32_e32 v71, v48, v73
	v_cvt_pk_bf16_f32 v71, v71, s0
	ds_write_b16 v70, v71
	v_mul_f32_e32 v71, 0xbfb8aa3b, v49
	v_exp_f32_e32 v71, v71
	s_nop 0
	v_add_f32_e32 v71, 1.0, v71
	s_nop 0
	v_rcp_f32_e32 v73, v71
	s_nop 0
	v_mul_f32_e32 v71, v49, v73
	v_cvt_pk_bf16_f32 v71, v71, s0
	ds_write_b16 v70, v71 offset:272
	v_mul_f32_e32 v71, 0xbfb8aa3b, v50
	v_exp_f32_e32 v71, v71
	s_nop 0
	v_add_f32_e32 v71, 1.0, v71
	s_nop 0
	v_rcp_f32_e32 v73, v71
	s_nop 0
	v_mul_f32_e32 v71, v50, v73
	v_cvt_pk_bf16_f32 v71, v71, s0
	ds_write_b16 v70, v71 offset:544
	v_mul_f32_e32 v71, 0xbfb8aa3b, v51
	v_exp_f32_e32 v71, v71
	s_nop 0
	v_add_f32_e32 v71, 1.0, v71
	s_nop 0
	v_rcp_f32_e32 v73, v71
	s_nop 0
	v_mul_f32_e32 v71, v51, v73
	v_cvt_pk_bf16_f32 v71, v71, s0
	ds_write_b16 v70, v71 offset:816
	v_mul_f32_e32 v71, 0xbfb8aa3b, v52
	v_exp_f32_e32 v71, v71
	s_nop 0
	v_add_f32_e32 v71, 1.0, v71
	s_nop 0
	v_rcp_f32_e32 v73, v71
	s_nop 0
	v_mul_f32_e32 v71, v52, v73
	v_cvt_pk_bf16_f32 v71, v71, s0
	ds_write_b16 v70, v71 offset:2176
	v_mul_f32_e32 v71, 0xbfb8aa3b, v53
	v_exp_f32_e32 v71, v71
	s_nop 0
	v_add_f32_e32 v71, 1.0, v71
	s_nop 0
	v_rcp_f32_e32 v73, v71
	s_nop 0
	v_mul_f32_e32 v71, v53, v73
	v_cvt_pk_bf16_f32 v71, v71, s0
	ds_write_b16 v70, v71 offset:2448
	v_mul_f32_e32 v71, 0xbfb8aa3b, v54
	v_exp_f32_e32 v71, v71
	s_nop 0
	v_add_f32_e32 v71, 1.0, v71
	s_nop 0
	v_rcp_f32_e32 v73, v71
	s_nop 0
	v_mul_f32_e32 v71, v54, v73
	v_cvt_pk_bf16_f32 v71, v71, s0
	ds_write_b16 v70, v71 offset:2720
	v_mul_f32_e32 v71, 0xbfb8aa3b, v55
	v_exp_f32_e32 v71, v71
	s_nop 0
	v_add_f32_e32 v71, 1.0, v71
	s_nop 0
	v_rcp_f32_e32 v73, v71
	s_nop 0
	v_mul_f32_e32 v71, v55, v73
	v_cvt_pk_bf16_f32 v71, v71, s0
	ds_write_b16 v70, v71 offset:2992
	v_mul_f32_e32 v71, 0xbfb8aa3b, v56
	v_exp_f32_e32 v71, v71
	s_nop 0
	v_add_f32_e32 v71, 1.0, v71
	s_nop 0
	v_rcp_f32_e32 v73, v71
	s_nop 0
	v_mul_f32_e32 v71, v56, v73
	v_cvt_pk_bf16_f32 v71, v71, s0
	ds_write_b16 v70, v71 offset:4352
	v_mul_f32_e32 v71, 0xbfb8aa3b, v57
	v_exp_f32_e32 v71, v71
	s_nop 0
	v_add_f32_e32 v71, 1.0, v71
	s_nop 0
	v_rcp_f32_e32 v73, v71
	s_nop 0
	v_mul_f32_e32 v71, v57, v73
	v_cvt_pk_bf16_f32 v71, v71, s0
	ds_write_b16 v70, v71 offset:4624
	v_mul_f32_e32 v71, 0xbfb8aa3b, v58
	v_exp_f32_e32 v71, v71
	s_nop 0
	v_add_f32_e32 v71, 1.0, v71
	s_nop 0
	v_rcp_f32_e32 v73, v71
	s_nop 0
	v_mul_f32_e32 v71, v58, v73
	v_cvt_pk_bf16_f32 v71, v71, s0
	ds_write_b16 v70, v71 offset:4896
	v_mul_f32_e32 v71, 0xbfb8aa3b, v59
	v_exp_f32_e32 v71, v71
	s_nop 0
	v_add_f32_e32 v71, 1.0, v71
	s_nop 0
	v_rcp_f32_e32 v73, v71
	s_nop 0
	v_mul_f32_e32 v71, v59, v73
	v_cvt_pk_bf16_f32 v71, v71, s0
	ds_write_b16 v70, v71 offset:5168
	v_mul_f32_e32 v71, 0xbfb8aa3b, v60
	v_exp_f32_e32 v71, v71
	s_nop 0
	v_add_f32_e32 v71, 1.0, v71
	s_nop 0
	v_rcp_f32_e32 v73, v71
	s_nop 0
	v_mul_f32_e32 v71, v60, v73
	v_cvt_pk_bf16_f32 v71, v71, s0
	ds_write_b16 v70, v71 offset:6528
	v_mul_f32_e32 v71, 0xbfb8aa3b, v61
	v_exp_f32_e32 v71, v71
	s_nop 0
	v_add_f32_e32 v71, 1.0, v71
	s_nop 0
	v_rcp_f32_e32 v73, v71
	s_nop 0
	v_mul_f32_e32 v71, v61, v73
	v_cvt_pk_bf16_f32 v71, v71, s0
	ds_write_b16 v70, v71 offset:6800
	v_mul_f32_e32 v71, 0xbfb8aa3b, v62
	v_exp_f32_e32 v71, v71
	s_nop 0
	v_add_f32_e32 v71, 1.0, v71
	s_nop 0
	v_rcp_f32_e32 v73, v71
	s_nop 0
	v_mul_f32_e32 v71, v62, v73
	v_cvt_pk_bf16_f32 v71, v71, s0
	ds_write_b16 v70, v71 offset:7072
	v_mul_f32_e32 v71, 0xbfb8aa3b, v63
	v_exp_f32_e32 v71, v71
	s_nop 0
	v_add_f32_e32 v71, 1.0, v71
	s_nop 0
	v_rcp_f32_e32 v73, v71
	s_nop 0
	v_mul_f32_e32 v71, v63, v73
	v_cvt_pk_bf16_f32 v71, v71, s0
	ds_write_b16 v70, v71 offset:7344
	v_mul_f32_e32 v71, 0xbfb8aa3b, v32
	v_exp_f32_e32 v71, v71
	s_nop 0
	v_add_f32_e32 v71, 1.0, v71
	s_nop 0
	v_rcp_f32_e32 v73, v71
	s_nop 0
	v_mul_f32_e32 v71, v32, v73
	v_cvt_pk_bf16_f32 v71, v71, s0
	ds_write_b16 v70, v71 offset:64
	v_mul_f32_e32 v71, 0xbfb8aa3b, v33
	v_exp_f32_e32 v71, v71
	s_nop 0
	v_add_f32_e32 v71, 1.0, v71
	s_nop 0
	v_rcp_f32_e32 v73, v71
	s_nop 0
	v_mul_f32_e32 v71, v33, v73
	v_cvt_pk_bf16_f32 v71, v71, s0
	ds_write_b16 v70, v71 offset:336
	v_mul_f32_e32 v71, 0xbfb8aa3b, v34
	v_exp_f32_e32 v71, v71
	s_nop 0
	v_add_f32_e32 v71, 1.0, v71
	s_nop 0
	v_rcp_f32_e32 v73, v71
	s_nop 0
	v_mul_f32_e32 v71, v34, v73
	v_cvt_pk_bf16_f32 v71, v71, s0
	ds_write_b16 v70, v71 offset:608
	v_mul_f32_e32 v71, 0xbfb8aa3b, v35
	v_exp_f32_e32 v71, v71
	s_nop 0
	v_add_f32_e32 v71, 1.0, v71
	s_nop 0
	v_rcp_f32_e32 v73, v71
	s_nop 0
	v_mul_f32_e32 v71, v35, v73
	v_cvt_pk_bf16_f32 v71, v71, s0
	ds_write_b16 v70, v71 offset:880
	v_mul_f32_e32 v71, 0xbfb8aa3b, v36
	v_exp_f32_e32 v71, v71
	s_nop 0
	v_add_f32_e32 v71, 1.0, v71
	s_nop 0
	v_rcp_f32_e32 v73, v71
	s_nop 0
	v_mul_f32_e32 v71, v36, v73
	v_cvt_pk_bf16_f32 v71, v71, s0
	ds_write_b16 v70, v71 offset:2240
	v_mul_f32_e32 v71, 0xbfb8aa3b, v37
	v_exp_f32_e32 v71, v71
	s_nop 0
	v_add_f32_e32 v71, 1.0, v71
	s_nop 0
	v_rcp_f32_e32 v73, v71
	s_nop 0
	v_mul_f32_e32 v71, v37, v73
	v_cvt_pk_bf16_f32 v71, v71, s0
	ds_write_b16 v70, v71 offset:2512
	v_mul_f32_e32 v71, 0xbfb8aa3b, v38
	v_exp_f32_e32 v71, v71
	s_nop 0
	v_add_f32_e32 v71, 1.0, v71
	s_nop 0
	v_rcp_f32_e32 v73, v71
	s_nop 0
	v_mul_f32_e32 v71, v38, v73
	v_cvt_pk_bf16_f32 v71, v71, s0
	ds_write_b16 v70, v71 offset:2784
	v_mul_f32_e32 v71, 0xbfb8aa3b, v39
	v_exp_f32_e32 v71, v71
	s_nop 0
	v_add_f32_e32 v71, 1.0, v71
	s_nop 0
	v_rcp_f32_e32 v73, v71
	s_nop 0
	v_mul_f32_e32 v71, v39, v73
	v_cvt_pk_bf16_f32 v71, v71, s0
	ds_write_b16 v70, v71 offset:3056
	v_mul_f32_e32 v71, 0xbfb8aa3b, v40
	v_exp_f32_e32 v71, v71
	s_nop 0
	v_add_f32_e32 v71, 1.0, v71
	s_nop 0
	v_rcp_f32_e32 v73, v71
	s_nop 0
	v_mul_f32_e32 v71, v40, v73
	v_cvt_pk_bf16_f32 v71, v71, s0
	ds_write_b16 v70, v71 offset:4416
	v_mul_f32_e32 v71, 0xbfb8aa3b, v41
	v_exp_f32_e32 v71, v71
	s_nop 0
	v_add_f32_e32 v71, 1.0, v71
	s_nop 0
	v_rcp_f32_e32 v73, v71
	s_nop 0
	v_mul_f32_e32 v71, v41, v73
	v_cvt_pk_bf16_f32 v71, v71, s0
	ds_write_b16 v70, v71 offset:4688
	v_mul_f32_e32 v71, 0xbfb8aa3b, v42
	v_exp_f32_e32 v71, v71
	s_nop 0
	v_add_f32_e32 v71, 1.0, v71
	s_nop 0
	v_rcp_f32_e32 v73, v71
	s_nop 0
	v_mul_f32_e32 v71, v42, v73
	v_cvt_pk_bf16_f32 v71, v71, s0
	ds_write_b16 v70, v71 offset:4960
	v_mul_f32_e32 v71, 0xbfb8aa3b, v43
	v_exp_f32_e32 v71, v71
	s_nop 0
	v_add_f32_e32 v71, 1.0, v71
	s_nop 0
	v_rcp_f32_e32 v73, v71
	s_nop 0
	v_mul_f32_e32 v71, v43, v73
	v_cvt_pk_bf16_f32 v71, v71, s0
	ds_write_b16 v70, v71 offset:5232
	v_mul_f32_e32 v71, 0xbfb8aa3b, v44
	v_exp_f32_e32 v71, v71
	s_nop 0
	v_add_f32_e32 v71, 1.0, v71
	s_nop 0
	v_rcp_f32_e32 v73, v71
	s_nop 0
	v_mul_f32_e32 v71, v44, v73
	v_cvt_pk_bf16_f32 v71, v71, s0
	ds_write_b16 v70, v71 offset:6592
	v_mul_f32_e32 v71, 0xbfb8aa3b, v45
	v_exp_f32_e32 v71, v71
	s_nop 0
	v_add_f32_e32 v71, 1.0, v71
	s_nop 0
	v_rcp_f32_e32 v73, v71
	s_nop 0
	v_mul_f32_e32 v71, v45, v73
	v_cvt_pk_bf16_f32 v71, v71, s0
	ds_write_b16 v70, v71 offset:6864
	v_mul_f32_e32 v71, 0xbfb8aa3b, v46
	v_exp_f32_e32 v71, v71
	s_nop 0
	v_add_f32_e32 v71, 1.0, v71
	s_nop 0
	v_rcp_f32_e32 v73, v71
	s_nop 0
	v_mul_f32_e32 v71, v46, v73
	v_cvt_pk_bf16_f32 v71, v71, s0
	ds_write_b16 v70, v71 offset:7136
	v_mul_f32_e32 v71, 0xbfb8aa3b, v47
	v_exp_f32_e32 v71, v71
	s_nop 0
	v_add_f32_e32 v71, 1.0, v71
	s_nop 0
	v_rcp_f32_e32 v73, v71
	s_nop 0
	v_mul_f32_e32 v71, v47, v73
	v_cvt_pk_bf16_f32 v71, v71, s0
	ds_write_b16 v70, v71 offset:7408
	v_mul_f32_e32 v71, 0xbfb8aa3b, v16
	v_exp_f32_e32 v71, v71
	s_nop 0
	v_add_f32_e32 v71, 1.0, v71
	s_nop 0
	v_rcp_f32_e32 v73, v71
	s_nop 0
	v_mul_f32_e32 v71, v16, v73
	v_cvt_pk_bf16_f32 v71, v71, s0
	ds_write_b16 v70, v71 offset:8704
	v_mul_f32_e32 v71, 0xbfb8aa3b, v17
	v_exp_f32_e32 v71, v71
	s_nop 0
	v_add_f32_e32 v71, 1.0, v71
	s_nop 0
	v_rcp_f32_e32 v73, v71
	s_nop 0
	v_mul_f32_e32 v71, v17, v73
	v_cvt_pk_bf16_f32 v71, v71, s0
	ds_write_b16 v70, v71 offset:8976
	v_mul_f32_e32 v71, 0xbfb8aa3b, v18
	v_exp_f32_e32 v71, v71
	s_nop 0
	v_add_f32_e32 v71, 1.0, v71
	s_nop 0
	v_rcp_f32_e32 v73, v71
	s_nop 0
	v_mul_f32_e32 v71, v18, v73
	v_cvt_pk_bf16_f32 v71, v71, s0
	ds_write_b16 v70, v71 offset:9248
	v_mul_f32_e32 v71, 0xbfb8aa3b, v19
	v_exp_f32_e32 v71, v71
	s_nop 0
	v_add_f32_e32 v71, 1.0, v71
	s_nop 0
	v_rcp_f32_e32 v73, v71
	s_nop 0
	v_mul_f32_e32 v71, v19, v73
	v_cvt_pk_bf16_f32 v71, v71, s0
	ds_write_b16 v70, v71 offset:9520
	v_mul_f32_e32 v71, 0xbfb8aa3b, v20
	v_exp_f32_e32 v71, v71
	s_nop 0
	v_add_f32_e32 v71, 1.0, v71
	s_nop 0
	v_rcp_f32_e32 v73, v71
	s_nop 0
	v_mul_f32_e32 v71, v20, v73
	v_cvt_pk_bf16_f32 v71, v71, s0
	ds_write_b16 v70, v71 offset:10880
	v_mul_f32_e32 v71, 0xbfb8aa3b, v21
	v_exp_f32_e32 v71, v71
	s_nop 0
	v_add_f32_e32 v71, 1.0, v71
	s_nop 0
	v_rcp_f32_e32 v73, v71
	s_nop 0
	v_mul_f32_e32 v71, v21, v73
	v_cvt_pk_bf16_f32 v71, v71, s0
	ds_write_b16 v70, v71 offset:11152
	v_mul_f32_e32 v71, 0xbfb8aa3b, v22
	v_exp_f32_e32 v71, v71
	s_nop 0
	v_add_f32_e32 v71, 1.0, v71
	s_nop 0
	v_rcp_f32_e32 v73, v71
	s_nop 0
	v_mul_f32_e32 v71, v22, v73
	v_cvt_pk_bf16_f32 v71, v71, s0
	ds_write_b16 v70, v71 offset:11424
	v_mul_f32_e32 v71, 0xbfb8aa3b, v23
	v_exp_f32_e32 v71, v71
	s_nop 0
	v_add_f32_e32 v71, 1.0, v71
	s_nop 0
	v_rcp_f32_e32 v73, v71
	s_nop 0
	v_mul_f32_e32 v71, v23, v73
	v_cvt_pk_bf16_f32 v71, v71, s0
	ds_write_b16 v70, v71 offset:11696
	v_mul_f32_e32 v71, 0xbfb8aa3b, v24
	v_exp_f32_e32 v71, v71
	s_nop 0
	v_add_f32_e32 v71, 1.0, v71
	s_nop 0
	v_rcp_f32_e32 v73, v71
	s_nop 0
	v_mul_f32_e32 v71, v24, v73
	v_cvt_pk_bf16_f32 v71, v71, s0
	ds_write_b16 v70, v71 offset:13056
	v_mul_f32_e32 v71, 0xbfb8aa3b, v25
	v_exp_f32_e32 v71, v71
	s_nop 0
	v_add_f32_e32 v71, 1.0, v71
	s_nop 0
	v_rcp_f32_e32 v73, v71
	s_nop 0
	v_mul_f32_e32 v71, v25, v73
	v_cvt_pk_bf16_f32 v71, v71, s0
	ds_write_b16 v70, v71 offset:13328
	v_mul_f32_e32 v71, 0xbfb8aa3b, v26
	v_exp_f32_e32 v71, v71
	s_nop 0
	v_add_f32_e32 v71, 1.0, v71
	s_nop 0
	v_rcp_f32_e32 v73, v71
	s_nop 0
	v_mul_f32_e32 v71, v26, v73
	v_cvt_pk_bf16_f32 v71, v71, s0
	ds_write_b16 v70, v71 offset:13600
	v_mul_f32_e32 v71, 0xbfb8aa3b, v27
	v_exp_f32_e32 v71, v71
	s_nop 0
	v_add_f32_e32 v71, 1.0, v71
	s_nop 0
	v_rcp_f32_e32 v73, v71
	s_nop 0
	v_mul_f32_e32 v71, v27, v73
	v_cvt_pk_bf16_f32 v71, v71, s0
	ds_write_b16 v70, v71 offset:13872
	v_mul_f32_e32 v71, 0xbfb8aa3b, v28
	v_exp_f32_e32 v71, v71
	s_nop 0
	v_add_f32_e32 v71, 1.0, v71
	s_nop 0
	v_rcp_f32_e32 v73, v71
	s_nop 0
	v_mul_f32_e32 v71, v28, v73
	v_cvt_pk_bf16_f32 v71, v71, s0
	ds_write_b16 v70, v71 offset:15232
	v_mul_f32_e32 v71, 0xbfb8aa3b, v29
	v_exp_f32_e32 v71, v71
	s_nop 0
	v_add_f32_e32 v71, 1.0, v71
	s_nop 0
	v_rcp_f32_e32 v73, v71
	s_nop 0
	v_mul_f32_e32 v71, v29, v73
	v_cvt_pk_bf16_f32 v71, v71, s0
	ds_write_b16 v70, v71 offset:15504
	v_mul_f32_e32 v71, 0xbfb8aa3b, v30
	v_exp_f32_e32 v71, v71
	s_nop 0
	v_add_f32_e32 v71, 1.0, v71
	s_nop 0
	v_rcp_f32_e32 v73, v71
	s_nop 0
	v_mul_f32_e32 v71, v30, v73
	v_cvt_pk_bf16_f32 v71, v71, s0
	ds_write_b16 v70, v71 offset:15776
	v_mul_f32_e32 v71, 0xbfb8aa3b, v31
	v_exp_f32_e32 v71, v71
	s_nop 0
	v_add_f32_e32 v71, 1.0, v71
	s_nop 0
	v_rcp_f32_e32 v73, v71
	s_nop 0
	v_mul_f32_e32 v71, v31, v73
	v_cvt_pk_bf16_f32 v71, v71, s0
	ds_write_b16 v70, v71 offset:16048
	v_mul_f32_e32 v71, 0xbfb8aa3b, v0
	v_exp_f32_e32 v71, v71
	s_nop 0
	v_add_f32_e32 v71, 1.0, v71
	s_nop 0
	v_rcp_f32_e32 v73, v71
	s_nop 0
	v_mul_f32_e32 v71, v0, v73
	v_cvt_pk_bf16_f32 v71, v71, s0
	ds_write_b16 v70, v71 offset:8768
	v_mul_f32_e32 v71, 0xbfb8aa3b, v1
	v_exp_f32_e32 v71, v71
	s_nop 0
	v_add_f32_e32 v71, 1.0, v71
	s_nop 0
	v_rcp_f32_e32 v73, v71
	s_nop 0
	v_mul_f32_e32 v71, v1, v73
	v_cvt_pk_bf16_f32 v71, v71, s0
	ds_write_b16 v70, v71 offset:9040
	v_mul_f32_e32 v71, 0xbfb8aa3b, v2
	v_exp_f32_e32 v71, v71
	s_nop 0
	v_add_f32_e32 v71, 1.0, v71
	s_nop 0
	v_rcp_f32_e32 v73, v71
	s_nop 0
	v_mul_f32_e32 v71, v2, v73
	v_cvt_pk_bf16_f32 v71, v71, s0
	ds_write_b16 v70, v71 offset:9312
	v_mul_f32_e32 v71, 0xbfb8aa3b, v3
	v_exp_f32_e32 v71, v71
	s_nop 0
	v_add_f32_e32 v71, 1.0, v71
	s_nop 0
	v_rcp_f32_e32 v73, v71
	s_nop 0
	v_mul_f32_e32 v71, v3, v73
	v_cvt_pk_bf16_f32 v71, v71, s0
	ds_write_b16 v70, v71 offset:9584
	v_mul_f32_e32 v71, 0xbfb8aa3b, v4
	v_exp_f32_e32 v71, v71
	s_nop 0
	v_add_f32_e32 v71, 1.0, v71
	s_nop 0
	v_rcp_f32_e32 v73, v71
	s_nop 0
	v_mul_f32_e32 v71, v4, v73
	v_cvt_pk_bf16_f32 v71, v71, s0
	ds_write_b16 v70, v71 offset:10944
	v_mul_f32_e32 v71, 0xbfb8aa3b, v5
	v_exp_f32_e32 v71, v71
	s_nop 0
	v_add_f32_e32 v71, 1.0, v71
	s_nop 0
	v_rcp_f32_e32 v73, v71
	s_nop 0
	v_mul_f32_e32 v71, v5, v73
	v_cvt_pk_bf16_f32 v71, v71, s0
	ds_write_b16 v70, v71 offset:11216
	v_mul_f32_e32 v71, 0xbfb8aa3b, v6
	v_exp_f32_e32 v71, v71
	s_nop 0
	v_add_f32_e32 v71, 1.0, v71
	s_nop 0
	v_rcp_f32_e32 v73, v71
	s_nop 0
	v_mul_f32_e32 v71, v6, v73
	v_cvt_pk_bf16_f32 v71, v71, s0
	ds_write_b16 v70, v71 offset:11488
	v_mul_f32_e32 v71, 0xbfb8aa3b, v7
	v_exp_f32_e32 v71, v71
	s_nop 0
	v_add_f32_e32 v71, 1.0, v71
	s_nop 0
	v_rcp_f32_e32 v73, v71
	s_nop 0
	v_mul_f32_e32 v71, v7, v73
	v_cvt_pk_bf16_f32 v71, v71, s0
	ds_write_b16 v70, v71 offset:11760
	v_mul_f32_e32 v71, 0xbfb8aa3b, v8
	v_exp_f32_e32 v71, v71
	s_nop 0
	v_add_f32_e32 v71, 1.0, v71
	s_nop 0
	v_rcp_f32_e32 v73, v71
	s_nop 0
	v_mul_f32_e32 v71, v8, v73
	v_cvt_pk_bf16_f32 v71, v71, s0
	ds_write_b16 v70, v71 offset:13120
	v_mul_f32_e32 v71, 0xbfb8aa3b, v9
	v_exp_f32_e32 v71, v71
	s_nop 0
	v_add_f32_e32 v71, 1.0, v71
	s_nop 0
	v_rcp_f32_e32 v73, v71
	s_nop 0
	v_mul_f32_e32 v71, v9, v73
	v_cvt_pk_bf16_f32 v71, v71, s0
	ds_write_b16 v70, v71 offset:13392
	v_mul_f32_e32 v71, 0xbfb8aa3b, v10
	v_exp_f32_e32 v71, v71
	s_nop 0
	v_add_f32_e32 v71, 1.0, v71
	s_nop 0
	v_rcp_f32_e32 v73, v71
	s_nop 0
	v_mul_f32_e32 v71, v10, v73
	v_cvt_pk_bf16_f32 v71, v71, s0
	ds_write_b16 v70, v71 offset:13664
	v_mul_f32_e32 v71, 0xbfb8aa3b, v11
	v_exp_f32_e32 v71, v71
	s_nop 0
	v_add_f32_e32 v71, 1.0, v71
	s_nop 0
	v_rcp_f32_e32 v73, v71
	s_nop 0
	v_mul_f32_e32 v71, v11, v73
	v_cvt_pk_bf16_f32 v71, v71, s0
	ds_write_b16 v70, v71 offset:13936
	v_mul_f32_e32 v71, 0xbfb8aa3b, v12
	v_exp_f32_e32 v71, v71
	s_nop 0
	v_add_f32_e32 v71, 1.0, v71
	s_nop 0
	v_rcp_f32_e32 v73, v71
	s_nop 0
	v_mul_f32_e32 v71, v12, v73
	v_cvt_pk_bf16_f32 v71, v71, s0
	ds_write_b16 v70, v71 offset:15296
	v_mul_f32_e32 v71, 0xbfb8aa3b, v13
	v_exp_f32_e32 v71, v71
	s_nop 0
	v_add_f32_e32 v71, 1.0, v71
	s_nop 0
	v_rcp_f32_e32 v73, v71
	s_nop 0
	v_mul_f32_e32 v71, v13, v73
	v_cvt_pk_bf16_f32 v71, v71, s0
	ds_write_b16 v70, v71 offset:15568
	v_mul_f32_e32 v71, 0xbfb8aa3b, v14
	v_exp_f32_e32 v71, v71
	s_nop 0
	v_add_f32_e32 v71, 1.0, v71
	s_nop 0
	v_rcp_f32_e32 v73, v71
	s_nop 0
	v_mul_f32_e32 v71, v14, v73
	v_cvt_pk_bf16_f32 v71, v71, s0
	ds_write_b16 v70, v71 offset:15840
	v_mul_f32_e32 v70, 0xbfb8aa3b, v15
	v_exp_f32_e32 v70, v70
	s_nop 0
	v_add_f32_e32 v70, 1.0, v70
	s_nop 0
	v_rcp_f32_e32 v72, v70
	s_nop 0
	v_mul_f32_e32 v71, v15, v72
	v_mov_b32_e32 v72, v69

.LBB0_521:
	s_nop 3
	v_and_b32_e32 v2, 64, v75
	v_xor_b32_e32 v1, 1, v75
	v_add_u32_e32 v2, 64, v2
	v_cmp_lt_i32_e32 vcc, v1, v2
	v_lshlrev_b32_e32 v0, 3, v76
	v_and_b32_e32 v44, 0x1f8, v0
	v_cndmask_b32_e32 v1, v75, v1, vcc
	v_lshlrev_b32_e32 v77, 2, v1
	v_xor_b32_e32 v1, 2, v75
	v_cmp_lt_i32_e32 vcc, v1, v2
	v_lshlrev_b32_e32 v0, 2, v44
	v_readlane_b32 s36, v254, 13
	v_cndmask_b32_e32 v1, v75, v1, vcc
	v_lshlrev_b32_e32 v78, 2, v1
	v_xor_b32_e32 v1, 4, v75
	v_cmp_lt_i32_e32 vcc, v1, v2
	v_readlane_b32 s12, v255, 29
	v_lshlrev_b32_e32 v42, 1, v44
	v_cndmask_b32_e32 v1, v75, v1, vcc
	v_lshlrev_b32_e32 v79, 2, v1
	v_readlane_b32 s44, v254, 21
	v_readlane_b32 s45, v254, 22
	v_mov_b32_e32 v1, v43
	v_readlane_b32 s14, v255, 31
	v_readlane_b32 s15, v255, 32
	v_readlane_b32 s24, v255, 41
	v_readlane_b32 s25, v255, 42
	v_readlane_b32 s26, v255, 43
	v_readlane_b32 s27, v255, 44
	v_or_b32_e32 v2, 0x1000, v0
	v_mov_b32_e32 v3, v43
	s_mov_b32 s6, 0
	v_lshl_add_u64 v[46:47], s[44:45], 0, v[42:43]
	v_lshl_add_u64 v[48:49], s[14:15], 0, v[0:1]
	v_lshl_add_u64 v[50:51], s[14:15], 0, v[2:3]
	v_lshl_add_u64 v[52:53], s[24:25], 0, v[0:1]
	v_lshl_add_u64 v[54:55], s[26:27], 0, v[0:1]
	s_waitcnt lgkmcnt(0)
	s_barrier
	v_readlane_b32 s37, v254, 14
	v_readlane_b32 s38, v254, 15
	v_readlane_b32 s39, v254, 16
	v_readlane_b32 s40, v254, 17
	v_readlane_b32 s41, v254, 18
	v_readlane_b32 s42, v254, 19
	v_readlane_b32 s43, v254, 20
	v_readlane_b32 s46, v254, 23
	v_readlane_b32 s47, v254, 24
	v_readlane_b32 s48, v254, 25
	v_readlane_b32 s49, v254, 26
	v_readlane_b32 s50, v254, 27
	v_readlane_b32 s51, v254, 28
	v_readlane_b32 s13, v255, 30
	v_readlane_b32 s16, v255, 33
	v_readlane_b32 s17, v255, 34
	v_readlane_b32 s18, v255, 35
	v_readlane_b32 s19, v255, 36
	v_readlane_b32 s20, v255, 37
	v_readlane_b32 s21, v255, 38
	v_readlane_b32 s22, v255, 39
	v_readlane_b32 s23, v255, 40
	global_load_dwordx4 v[200:203], v[52:53], off offset:16
	global_load_dwordx4 v[204:207], v[52:53], off
	global_load_dwordx4 v[208:211], v[54:55], off offset:16
	global_load_dwordx4 v[212:215], v[54:55], off
	global_load_dwordx4 v[216:219], v[50:51], off offset:16
	global_load_dwordx4 v[220:223], v[50:51], off
	s_mov_b32 s98, s6
	v_add_u32_e32 v88, s98, v76
	v_ashrrev_i32_e32 v87, 6, v88
	v_add_u32_e32 v84, s31, v87
	v_mad_i64_i32 v[88:89], s[4:5], v84, s2, v[46:47]
	v_and_b32_e32 v90, 0x7ff, v84
	global_load_dwordx4 v[128:131], v[88:89], off
	v_cmp_ne_u32_e32 vcc, 0, v90
	v_add_u32_e32 v85, -1, v84
	v_mov_b32_e32 v132, 0
	v_mov_b32_e32 v133, 0
	v_mov_b32_e32 v134, 0
	v_mov_b32_e32 v135, 0
	v_mov_b32_e32 v180, 0
	v_mov_b32_e32 v181, 0
	v_mov_b32_e32 v182, 0
	v_mov_b32_e32 v183, 0
	v_mov_b32_e32 v196, 0
	v_mov_b32_e32 v197, 0
	v_mov_b32_e32 v198, 0
	v_mov_b32_e32 v199, 0
	global_load_dwordx4 v[136:139], v[48:49], off offset:16
	global_load_dwordx4 v[140:143], v[48:49], off
	global_load_dwordx4 v[144:147], v[88:89], off offset:1024
	global_load_dwordx4 v[184:187], v[48:49], off offset:2064
	global_load_dwordx4 v[188:191], v[48:49], off offset:2048
	global_load_dwordx4 v[192:195], v[88:89], off offset:2048
	s_and_saveexec_b64 s[4:5], vcc
	s_cbranch_execz .Lprep_skipprev_2
	v_mad_i64_i32 v[90:91], s[8:9], v85, s2, v[46:47]
	global_load_dwordx4 v[132:135], v[90:91], off
	global_load_dwordx4 v[180:183], v[90:91], off offset:1024
	global_load_dwordx4 v[196:199], v[90:91], off offset:2048

.LBB0_522:
	s_cmp_eq_u32 s6, 0
	s_cbranch_scc1 .Lprep_first
	s_waitcnt vmcnt(5)
	s_branch .Lprep_go

.Lprep_go:
	v_mov_b32_e32 v8, v128
	v_mov_b32_e32 v9, v129
	v_mov_b32_e32 v10, v130
	v_mov_b32_e32 v11, v131
	v_mov_b32_e32 v4, v132
	v_mov_b32_e32 v5, v133
	v_mov_b32_e32 v6, v134
	v_mov_b32_e32 v7, v135
	v_mov_b32_e32 v12, v136
	v_mov_b32_e32 v13, v137
	v_mov_b32_e32 v14, v138
	v_mov_b32_e32 v15, v139
	v_mov_b32_e32 v16, v140
	v_mov_b32_e32 v17, v141
	v_mov_b32_e32 v18, v142
	v_mov_b32_e32 v19, v143
	v_mov_b32_e32 v28, v144
	v_mov_b32_e32 v29, v145
	v_mov_b32_e32 v30, v146
	v_mov_b32_e32 v31, v147
	v_mov_b32_e32 v20, v180
	v_mov_b32_e32 v21, v181
	v_mov_b32_e32 v22, v182
	v_mov_b32_e32 v23, v183
	v_mov_b32_e32 v32, v184
	v_mov_b32_e32 v33, v185
	v_mov_b32_e32 v34, v186
	v_mov_b32_e32 v35, v187
	v_mov_b32_e32 v36, v188
	v_mov_b32_e32 v37, v189
	v_mov_b32_e32 v38, v190
	v_mov_b32_e32 v39, v191
	v_mov_b32_e32 v24, v192
	v_mov_b32_e32 v25, v193
	v_mov_b32_e32 v26, v194
	v_mov_b32_e32 v27, v195
	v_mov_b32_e32 v0, v196
	v_mov_b32_e32 v1, v197
	v_mov_b32_e32 v2, v198
	v_mov_b32_e32 v3, v199
	v_mov_b32_e32 v56, v84
	v_mov_b32_e32 v58, v87
	s_cmpk_eq_i32 s6, 0x700
	s_cbranch_scc1 .Lprep_noload
	s_add_i32 s98, s6, 0x100
	v_add_u32_e32 v88, s98, v76
	v_ashrrev_i32_e32 v87, 6, v88
	v_add_u32_e32 v84, s31, v87
	v_mad_i64_i32 v[88:89], s[4:5], v84, s2, v[46:47]
	v_and_b32_e32 v90, 0x7ff, v84
	global_load_dwordx4 v[128:131], v[88:89], off
	v_cmp_ne_u32_e32 vcc, 0, v90
	v_add_u32_e32 v85, -1, v84
	v_mov_b32_e32 v132, 0
	v_mov_b32_e32 v133, 0
	v_mov_b32_e32 v134, 0
	v_mov_b32_e32 v135, 0
	v_mov_b32_e32 v180, 0
	v_mov_b32_e32 v181, 0
	v_mov_b32_e32 v182, 0
	v_mov_b32_e32 v183, 0
	v_mov_b32_e32 v196, 0
	v_mov_b32_e32 v197, 0
	v_mov_b32_e32 v198, 0
	v_mov_b32_e32 v199, 0
	global_load_dwordx4 v[136:139], v[48:49], off offset:16
	global_load_dwordx4 v[140:143], v[48:49], off
	global_load_dwordx4 v[144:147], v[88:89], off offset:1024
	global_load_dwordx4 v[184:187], v[48:49], off offset:2064
	global_load_dwordx4 v[188:191], v[48:49], off offset:2048
	global_load_dwordx4 v[192:195], v[88:89], off offset:2048
	s_and_saveexec_b64 s[4:5], vcc
	s_cbranch_execz .Lprep_skipprev_1
	v_mad_i64_i32 v[90:91], s[8:9], v85, s2, v[46:47]
	global_load_dwordx4 v[132:135], v[90:91], off
	global_load_dwordx4 v[180:183], v[90:91], off offset:1024
	global_load_dwordx4 v[196:199], v[90:91], off offset:2048

.Lprep_noload:
	v_lshlrev_b32_e32 v60, 16, v28
	v_and_b32_e32 v61, 0xffff0000, v28
	v_lshlrev_b32_e32 v28, 16, v29
	v_and_b32_e32 v29, 0xffff0000, v29
	v_lshlrev_b32_e32 v62, 16, v30
	v_and_b32_e32 v63, 0xffff0000, v30
	v_lshlrev_b32_e32 v64, 16, v31
	v_and_b32_e32 v65, 0xffff0000, v31
	v_lshlrev_b32_e32 v30, 16, v20
	v_and_b32_e32 v31, 0xffff0000, v20
	v_lshlrev_b32_e32 v20, 16, v21
	v_and_b32_e32 v21, 0xffff0000, v21
	v_lshlrev_b32_e32 v66, 16, v22
	v_and_b32_e32 v67, 0xffff0000, v22
	v_pk_add_f32 v[30:31], v[30:31], v[60:61] neg_lo:[0,1] neg_hi:[0,1]
	v_pk_add_f32 v[20:21], v[20:21], v[28:29] neg_lo:[0,1] neg_hi:[0,1]
	v_lshlrev_b32_e32 v22, 16, v23
	v_and_b32_e32 v23, 0xffff0000, v23
	v_pk_fma_f32 v[36:37], v[30:31], v[36:37], v[60:61]
	v_pk_fma_f32 v[30:31], v[20:21], v[38:39], v[28:29]
	v_pk_add_f32 v[20:21], v[66:67], v[62:63] neg_lo:[0,1] neg_hi:[0,1]
	v_lshlrev_b32_e32 v28, 16, v4
	v_pk_fma_f32 v[32:33], v[20:21], v[32:33], v[62:63]
	v_pk_add_f32 v[20:21], v[22:23], v[64:65] neg_lo:[0,1] neg_hi:[0,1]
	v_and_b32_e32 v29, 0xffff0000, v4
	v_pk_fma_f32 v[68:69], v[20:21], v[34:35], v[64:65]
	v_lshlrev_b32_e32 v20, 16, v8
	v_and_b32_e32 v21, 0xffff0000, v8
	v_lshlrev_b32_e32 v8, 16, v9
	v_and_b32_e32 v9, 0xffff0000, v9
	v_lshlrev_b32_e32 v4, 16, v5
	v_and_b32_e32 v5, 0xffff0000, v5
	v_lshlrev_b32_e32 v22, 16, v10
	v_and_b32_e32 v23, 0xffff0000, v10
	v_lshlrev_b32_e32 v34, 16, v6
	v_and_b32_e32 v35, 0xffff0000, v6
	v_pk_add_f32 v[4:5], v[4:5], v[8:9] neg_lo:[0,1] neg_hi:[0,1]
	v_lshlrev_b32_e32 v10, 16, v11
	v_and_b32_e32 v11, 0xffff0000, v11
	v_lshlrev_b32_e32 v6, 16, v7
	v_and_b32_e32 v7, 0xffff0000, v7
	v_pk_fma_f32 v[18:19], v[4:5], v[18:19], v[8:9]
	v_pk_add_f32 v[4:5], v[34:35], v[22:23] neg_lo:[0,1] neg_hi:[0,1]
	s_movk_i32 s4, 0x410
	v_pk_fma_f32 v[12:13], v[4:5], v[12:13], v[22:23]
	v_pk_add_f32 v[4:5], v[6:7], v[10:11] neg_lo:[0,1] neg_hi:[0,1]
	v_pk_add_f32 v[28:29], v[28:29], v[20:21] neg_lo:[0,1] neg_hi:[0,1]
	v_pk_fma_f32 v[14:15], v[4:5], v[14:15], v[10:11]
	v_mad_u64_u32 v[4:5], s[4:5], v58, s4, v[42:43]
	ds_read_b128 v[58:61], v4 offset:9216
	v_pk_fma_f32 v[16:17], v[28:29], v[16:17], v[20:21]
	v_lshlrev_b32_e32 v22, 16, v26
	v_and_b32_e32 v23, 0xffff0000, v26
	v_lshlrev_b32_e32 v20, 16, v27
	s_waitcnt lgkmcnt(0)
	v_lshlrev_b32_e32 v6, 16, v58
	v_and_b32_e32 v7, 0xffff0000, v58
	v_lshlrev_b32_e32 v8, 16, v59
	v_and_b32_e32 v9, 0xffff0000, v59
	v_lshlrev_b32_e32 v10, 16, v60
	v_and_b32_e32 v11, 0xffff0000, v60
	v_lshlrev_b32_e32 v4, 16, v61
	v_and_b32_e32 v5, 0xffff0000, v61
	v_mov_b32_e32 v58, v200
	v_mov_b32_e32 v59, v201
	v_mov_b32_e32 v60, v202
	v_mov_b32_e32 v61, v203
	v_mov_b32_e32 v62, v204
	v_mov_b32_e32 v63, v205
	v_mov_b32_e32 v64, v206
	v_mov_b32_e32 v65, v207
	v_and_b32_e32 v21, 0xffff0000, v27
	v_pk_add_f32 v[26:27], v[10:11], -1.0 op_sel_hi:[1,0]
	s_mov_b32 s4, 0xf800000
	v_lshlrev_b32_e32 v28, 16, v24
	v_and_b32_e32 v29, 0xffff0000, v24
	v_lshlrev_b32_e32 v24, 16, v25
	v_and_b32_e32 v25, 0xffff0000, v25
	v_ashrrev_i32_e32 v57, 31, v56
	s_addk_i32 s6, 0x100
	s_cmpk_lg_i32 s6, 0x800
	v_pk_mul_f32 v[66:67], v[68:69], v[60:61]
	v_pk_mul_f32 v[38:39], v[32:33], v[58:59]
	v_mov_b32_e32 v80, v208
	v_mov_b32_e32 v81, v209
	v_mov_b32_e32 v82, v210
	v_mov_b32_e32 v83, v211
	v_mov_b32_e32 v58, v212
	v_mov_b32_e32 v59, v213
	v_mov_b32_e32 v60, v214
	v_mov_b32_e32 v61, v215
	v_pk_mul_f32 v[64:65], v[30:31], v[64:65]
	v_pk_mul_f32 v[70:71], v[38:39], v[38:39]
	v_pk_mul_f32 v[34:35], v[66:67], v[66:67]
	v_pk_fma_f32 v[26:27], v[26:27], v[80:81], 1.0 op_sel_hi:[1,1,0]
	s_nop 0
	v_pk_mul_f32 v[26:27], v[32:33], v[26:27]
	v_pk_add_f32 v[32:33], v[8:9], -1.0 op_sel_hi:[1,0]
	v_pk_mul_f32 v[80:81], v[64:65], v[64:65]
	v_pk_fma_f32 v[32:33], v[32:33], v[60:61], 1.0 op_sel_hi:[1,1,0]
	v_pk_mul_f32 v[60:61], v[36:37], v[62:63]
	v_pk_mul_f32 v[30:31], v[30:31], v[32:33]
	v_pk_add_f32 v[32:33], v[6:7], -1.0 op_sel_hi:[1,0]
	v_pk_mul_f32 v[62:63], v[60:61], v[60:61]
	v_pk_fma_f32 v[32:33], v[32:33], v[58:59], 1.0 op_sel_hi:[1,1,0]
	s_nop 0
	v_pk_mul_f32 v[32:33], v[36:37], v[32:33]
	v_add_f32_e32 v36, v62, v63
	v_add_f32_e32 v36, v36, v80
	v_add_f32_e32 v36, v36, v81
	v_add_f32_e32 v36, v36, v70
	v_add_f32_e32 v36, v36, v71
	v_add_f32_e32 v34, v36, v34
	v_add_f32_e32 v34, v34, v35
	ds_bpermute_b32 v35, v77, v34
	v_lshlrev_b32_e32 v70, 16, v0
	v_and_b32_e32 v71, 0xffff0000, v0
	v_lshlrev_b32_e32 v0, 16, v1
	v_and_b32_e32 v1, 0xffff0000, v1
	s_waitcnt lgkmcnt(0)
	v_add_f32_e32 v34, v34, v35
	ds_bpermute_b32 v35, v78, v34
	v_pk_add_f32 v[0:1], v[0:1], v[24:25] neg_lo:[0,1] neg_hi:[0,1]
	v_pk_add_f32 v[70:71], v[70:71], v[28:29] neg_lo:[0,1] neg_hi:[0,1]
	s_waitcnt lgkmcnt(0)
	v_add_f32_e32 v34, v34, v35
	ds_bpermute_b32 v35, v79, v34
	s_waitcnt lgkmcnt(0)
	v_add_f32_e32 v34, v34, v35
	v_cmp_gt_f32_e32 vcc, s4, v34
	v_mul_f32_e32 v35, 0x4f800000, v34
	s_nop 0
	v_cndmask_b32_e32 v34, v34, v35, vcc
	v_sqrt_f32_e32 v35, v34
	s_nop 0
	v_add_u32_e32 v36, -1, v35
	v_fma_f32 v37, -v36, v35, v34
	v_cmp_ge_f32_e64 s[4:5], 0, v37
	v_add_u32_e32 v37, 1, v35
	s_nop 0
	v_cndmask_b32_e64 v36, v35, v36, s[4:5]
	v_fma_f32 v35, -v37, v35, v34
	v_cmp_lt_f32_e64 s[4:5], 0, v35
	s_nop 1
	v_cndmask_b32_e64 v35, v36, v37, s[4:5]
	v_mul_f32_e32 v36, 0x37800000, v35
	v_cndmask_b32_e32 v35, v35, v36, vcc
	v_cmp_class_f32_e32 vcc, v34, v73
	s_nop 1
	v_cndmask_b32_e32 v34, v35, v34, vcc
	v_max_f32_e32 v34, 0x2b8cbccc, v34
	v_div_scale_f32 v35, s[4:5], v34, v34, 1.0
	v_rcp_f32_e32 v36, v35
	s_nop 0
	v_fma_f32 v37, -v35, v36, 1.0
	v_fmac_f32_e32 v36, v37, v36
	v_div_scale_f32 v37, vcc, 1.0, v34, 1.0
	v_mul_f32_e32 v58, v37, v36
	v_fma_f32 v59, -v35, v58, v37
	v_fmac_f32_e32 v58, v59, v36
	v_fma_f32 v35, -v35, v58, v37
	v_div_fmas_f32 v35, v35, v36, v58
	v_div_fixup_f32 v58, v35, v34, 1.0
	v_pk_mul_f32 v[66:67], v[66:67], v[58:59] op_sel_hi:[1,0]
	v_pk_mul_f32 v[60:61], v[60:61], v[58:59] op_sel_hi:[1,0]
	v_pk_mul_f32 v[62:63], v[64:65], v[58:59] op_sel_hi:[1,0]
	v_pk_mul_f32 v[64:65], v[38:39], v[58:59] op_sel_hi:[1,0]
	v_pk_mul_f32 v[58:59], v[66:67], v[4:5]
	v_pk_add_f32 v[4:5], v[4:5], -1.0 op_sel_hi:[1,0]
	v_pk_mul_f32 v[34:35], v[60:61], v[6:7]
	v_pk_fma_f32 v[4:5], v[4:5], v[82:83], 1.0 op_sel_hi:[1,1,0]
	v_pk_mul_f32 v[36:37], v[62:63], v[8:9]
	v_pk_mul_f32 v[38:39], v[64:65], v[10:11]
	v_pk_mul_f32 v[68:69], v[68:69], v[4:5]
	v_mov_b32_e32 v4, v216
	v_mov_b32_e32 v5, v217
	v_mov_b32_e32 v6, v218
	v_mov_b32_e32 v7, v219
	v_mov_b32_e32 v8, v220
	v_mov_b32_e32 v9, v221
	v_mov_b32_e32 v10, v222
	v_mov_b32_e32 v11, v223
	v_pk_fma_f32 v[10:11], v[0:1], v[10:11], v[24:25]
	v_lshlrev_b32_e32 v0, 16, v2
	v_and_b32_e32 v1, 0xffff0000, v2
	v_pk_add_f32 v[0:1], v[0:1], v[22:23] neg_lo:[0,1] neg_hi:[0,1]
	v_cvt_pk_bf16_f32 v2, v12, v13
	v_pk_fma_f32 v[4:5], v[0:1], v[4:5], v[22:23]
	v_lshlrev_b32_e32 v0, 16, v3
	v_and_b32_e32 v1, 0xffff0000, v3
	v_pk_add_f32 v[0:1], v[0:1], v[20:21] neg_lo:[0,1] neg_hi:[0,1]
	v_cvt_pk_bf16_f32 v3, v14, v15
	v_pk_fma_f32 v[6:7], v[0:1], v[6:7], v[20:21]
	v_lshlrev_b64 v[20:21], 10, v[56:57]
	v_lshl_or_b32 v20, v44, 1, v20
	v_lshl_add_u64 v[22:23], s[58:59], 0, v[20:21]
	v_cvt_pk_bf16_f32 v0, v16, v17
	v_cvt_pk_bf16_f32 v1, v18, v19
	v_pk_fma_f32 v[8:9], v[70:71], v[8:9], v[28:29]
	global_store_dwordx4 v[22:23], v[0:3], off nt
	v_lshl_add_u64 v[12:13], s[60:61], 0, v[20:21]
	s_nop 0
	v_cvt_pk_bf16_f32 v0, v32, v33
	v_cvt_pk_bf16_f32 v1, v30, v31
	v_cvt_pk_bf16_f32 v2, v26, v27
	v_cvt_pk_bf16_f32 v3, v68, v69
	global_store_dwordx4 v[12:13], v[0:3], off nt
	v_lshl_add_u64 v[12:13], s[62:63], 0, v[20:21]
	s_nop 0
	v_cvt_pk_bf16_f32 v0, v8, v9
	v_cvt_pk_bf16_f32 v1, v10, v11
	v_cvt_pk_bf16_f32 v2, v4, v5
	v_cvt_pk_bf16_f32 v3, v6, v7
	global_store_dwordx4 v[12:13], v[0:3], off nt
	v_lshl_add_u64 v[4:5], s[64:65], 0, v[20:21]
	s_nop 0
	v_cvt_pk_bf16_f32 v0, v60, v61
	v_cvt_pk_bf16_f32 v1, v62, v63
	v_cvt_pk_bf16_f32 v2, v64, v65
	v_cvt_pk_bf16_f32 v3, v66, v67
	global_store_dwordx4 v[4:5], v[0:3], off nt
	v_lshl_add_u64 v[4:5], s[66:67], 0, v[20:21]
	s_nop 0
	v_cvt_pk_bf16_f32 v0, v34, v35
	v_cvt_pk_bf16_f32 v1, v36, v37
	v_cvt_pk_bf16_f32 v2, v38, v39
	v_cvt_pk_bf16_f32 v3, v58, v59
	global_store_dwordx4 v[4:5], v[0:3], off nt
	s_cbranch_scc0 .LBB0_438
	s_branch .LBB0_522
